# plus phase 11 SwiGLU epilogue: eight row-statistic loads issued together, per-row vmcnt(0) waits (which also waited for the previous store) dropped
# speedup vs baseline: 1.0042x; 1.0027x over previous
; __device__ __forceinline__ unsigned cvt_pk_bf16(float lo, float hi) { cvf32x2_t v = {lo, hi}; cvbf16x2_t b = __builtin_convertvector(v, cvbf16x2_t); return __builtin_bit_cast(unsigned, b); }
; __device__ __forceinline__ float fsigm(float x) { return __builtin_amdgcn_rcpf(1.f + __expf(-x)); }
; __device__ __forceinline__ float fsilu(float x) { return x * fsigm(x); }
; __device__ __forceinline__ float row_rs(const float* ssq, int row) { return ssq ? rsqrtf(ssq[row] * (1.f / 1024.f) + RMS_EPS) : 1.f; }
;     __device__ __forceinline__ void operator()(const f32x4 (&acc)[2][2][4][2], const Unit& u, int wr, int wc, int fr, int fq) const {
;     ...
;             for (int m = 0; m < 4; ++m) { const int row = row0 + ai * HALF + m * 16; const float rs = row_rs(ssq, row);
;                 u32x4 w; unsigned pk[4];
; #pragma unroll
;                 for (int n = 0; n < 2; ++n) { const f32x4 g = acc[ai][0][m][n] * rs, up = acc[ai][1][m][n] * rs;
;                     pk[2 * n] = cvt_pk_bf16(fsilu(g[0]) * up[0], fsilu(g[1]) * up[1]); pk[2 * n + 1] = cvt_pk_bf16(fsilu(g[2]) * up[2], fsilu(g[3]) * up[3]); }
;                 w.x = pk[0]; w.y = pk[1]; w.z = pk[2]; w.w = pk[3];
;                 st_wt16(H + (size_t)row * ldh + col0, w); }
.LBB0_1274:
	v_lshl_add_u32 v144, s6, 8, v152
	v_ashrrev_i32_e32 v145, 31, v144
	v_lshl_add_u64 v[150:151], v[144:145], 2, s[12:13]
	global_load_dword v145, v[150:151], off
	global_load_dword v176, v[150:151], off offset:64
	global_load_dword v177, v[150:151], off offset:128
	global_load_dword v178, v[150:151], off offset:192
	global_load_dword v179, v[150:151], off offset:512
	global_load_dword v180, v[150:151], off offset:576
	global_load_dword v181, v[150:151], off offset:640
	global_load_dword v182, v[150:151], off offset:704
	v_or_b32_e32 v162, 16, v144
	v_ashrrev_i32_e32 v163, 31, v162
	v_lshl_add_u64 v[164:165], v[162:163], 2, s[12:13]
	v_lshl_or_b32 v148, s7, 7, v154
	v_mov_b64_e32 v[146:147], s[56:57]
	v_ashrrev_i32_e32 v149, 31, v148
	v_mad_i64_i32 v[160:161], s[6:7], v144, s79, v[146:147]
	v_lshlrev_b64 v[148:149], 1, v[148:149]
	v_lshl_add_u64 v[160:161], v[160:161], 0, v[148:149]
	s_waitcnt vmcnt(0)
	v_fmamk_f32 v145, v145, 0x3a800000, v158
	v_mul_f32_e32 v159, 0x4b800000, v145
	v_cmp_gt_f32_e32 vcc, s77, v145
	s_nop 1
	v_cndmask_b32_e32 v145, v145, v159, vcc
	v_rsq_f32_e32 v145, v145
	s_nop 0
	v_mul_f32_e32 v159, 0x45800000, v145
	v_cndmask_b32_e32 v166, v145, v159, vcc
	v_pk_mul_f32 v[126:127], v[126:127], v[166:167] op_sel_hi:[1,0]
	v_pk_mul_f32 v[124:125], v[124:125], v[166:167] op_sel_hi:[1,0]
	v_pk_mul_f32 v[122:123], v[122:123], v[166:167] op_sel_hi:[1,0]
	v_pk_mul_f32 v[120:121], v[120:121], v[166:167] op_sel_hi:[1,0]
	v_pk_mul_f32 v[118:119], v[118:119], v[166:167] op_sel_hi:[1,0]
	v_pk_mul_f32 v[116:117], v[116:117], v[166:167] op_sel_hi:[1,0]
	v_pk_mul_f32 v[114:115], v[114:115], v[166:167] op_sel_hi:[1,0]
	v_pk_mul_f32 v[112:113], v[112:113], v[166:167] op_sel_hi:[1,0]
	v_mul_f32_e32 v145, 0xbfb8aa3b, v124
	v_mul_f32_e32 v159, 0xbfb8aa3b, v125
	v_mul_f32_e32 v163, 0xbfb8aa3b, v126
	v_mul_f32_e32 v166, 0xbfb8aa3b, v127
	v_mul_f32_e32 v167, 0xbfb8aa3b, v120
	v_mul_f32_e32 v168, 0xbfb8aa3b, v121
	v_mul_f32_e32 v169, 0xbfb8aa3b, v122
	v_mul_f32_e32 v170, 0xbfb8aa3b, v123
	v_exp_f32_e32 v145, v145
	v_exp_f32_e32 v159, v159
	v_exp_f32_e32 v163, v163
	v_exp_f32_e32 v166, v166
	v_exp_f32_e32 v167, v167
	v_exp_f32_e32 v168, v168
	v_exp_f32_e32 v169, v169
	v_exp_f32_e32 v170, v170
	v_add_f32_e32 v145, 1.0, v145
	v_add_f32_e32 v159, 1.0, v159
	v_add_f32_e32 v163, 1.0, v163
	v_add_f32_e32 v171, 1.0, v166
	v_add_f32_e32 v172, 1.0, v167
	v_add_f32_e32 v173, 1.0, v168
	v_add_f32_e32 v174, 1.0, v169
	v_add_f32_e32 v175, 1.0, v170
	v_rcp_f32_e32 v166, v145
	v_rcp_f32_e32 v167, v159
	v_rcp_f32_e32 v168, v163
	v_rcp_f32_e32 v169, v171
	v_rcp_f32_e32 v170, v172
	v_rcp_f32_e32 v171, v173
	v_rcp_f32_e32 v172, v174
	v_rcp_f32_e32 v173, v175
	v_pk_mul_f32 v[124:125], v[124:125], v[166:167]
	v_pk_mul_f32 v[126:127], v[126:127], v[168:169]
	v_pk_mul_f32 v[120:121], v[120:121], v[170:171]
	v_pk_mul_f32 v[122:123], v[122:123], v[172:173]
	v_pk_mul_f32 v[116:117], v[116:117], v[124:125]
	v_pk_mul_f32 v[118:119], v[118:119], v[126:127]
	v_pk_mul_f32 v[120:121], v[112:113], v[120:121]
	v_pk_mul_f32 v[122:123], v[114:115], v[122:123]
	v_cvt_pk_bf16_f32 v112, v116, v117
	v_cvt_pk_bf16_f32 v113, v118, v119
	v_cvt_pk_bf16_f32 v114, v120, v121
	v_cvt_pk_bf16_f32 v115, v122, v123
	global_store_dwordx4 v[160:161], v[112:115], off
	s_nop 1
	s_nop 0
	v_or_b32_e32 v112, 32, v144
	v_mad_i64_i32 v[114:115], s[6:7], v162, s79, v[146:147]
	v_lshl_add_u64 v[114:115], v[114:115], 0, v[148:149]
	v_fmamk_f32 v113, v176, 0x3a800000, v158
	v_mul_f32_e32 v116, 0x4b800000, v113
	v_cmp_gt_f32_e32 vcc, s77, v113
	s_nop 1
	v_cndmask_b32_e32 v113, v113, v116, vcc
	v_rsq_f32_e32 v118, v113
	v_ashrrev_i32_e32 v113, 31, v112
	v_lshl_add_u64 v[116:117], v[112:113], 2, s[12:13]
	v_mul_f32_e32 v113, 0x45800000, v118
	v_cndmask_b32_e32 v118, v118, v113, vcc
	v_pk_mul_f32 v[110:111], v[110:111], v[118:119] op_sel_hi:[1,0]
	v_pk_mul_f32 v[108:109], v[108:109], v[118:119] op_sel_hi:[1,0]
	v_pk_mul_f32 v[106:107], v[106:107], v[118:119] op_sel_hi:[1,0]
	v_pk_mul_f32 v[104:105], v[104:105], v[118:119] op_sel_hi:[1,0]
	v_pk_mul_f32 v[102:103], v[102:103], v[118:119] op_sel_hi:[1,0]
	v_pk_mul_f32 v[100:101], v[100:101], v[118:119] op_sel_hi:[1,0]
	v_pk_mul_f32 v[98:99], v[98:99], v[118:119] op_sel_hi:[1,0]
	v_pk_mul_f32 v[96:97], v[96:97], v[118:119] op_sel_hi:[1,0]
	v_mul_f32_e32 v113, 0xbfb8aa3b, v108
	v_mul_f32_e32 v118, 0xbfb8aa3b, v109
	v_mul_f32_e32 v119, 0xbfb8aa3b, v110
	v_mul_f32_e32 v120, 0xbfb8aa3b, v111
	v_mul_f32_e32 v121, 0xbfb8aa3b, v104
	v_mul_f32_e32 v122, 0xbfb8aa3b, v105
	v_mul_f32_e32 v123, 0xbfb8aa3b, v106
	v_mul_f32_e32 v124, 0xbfb8aa3b, v107
	v_exp_f32_e32 v113, v113
	v_exp_f32_e32 v118, v118
	v_exp_f32_e32 v119, v119
	v_exp_f32_e32 v120, v120
	v_exp_f32_e32 v121, v121
	v_exp_f32_e32 v122, v122
	v_exp_f32_e32 v123, v123
	v_exp_f32_e32 v124, v124
	v_add_f32_e32 v113, 1.0, v113
	v_add_f32_e32 v125, 1.0, v118
	v_add_f32_e32 v126, 1.0, v119
	v_add_f32_e32 v127, 1.0, v120
	v_add_f32_e32 v145, 1.0, v121
	v_add_f32_e32 v159, 1.0, v122
	v_add_f32_e32 v160, 1.0, v123
	v_add_f32_e32 v161, 1.0, v124
	v_rcp_f32_e32 v118, v113
	v_rcp_f32_e32 v119, v125
	v_rcp_f32_e32 v120, v126
	v_rcp_f32_e32 v121, v127
	v_rcp_f32_e32 v122, v145
	v_rcp_f32_e32 v123, v159
	v_rcp_f32_e32 v124, v160
	v_rcp_f32_e32 v125, v161
	v_pk_mul_f32 v[108:109], v[108:109], v[118:119]
	v_pk_mul_f32 v[110:111], v[110:111], v[120:121]
	v_pk_mul_f32 v[104:105], v[104:105], v[122:123]
	v_pk_mul_f32 v[106:107], v[106:107], v[124:125]
	v_pk_mul_f32 v[100:101], v[100:101], v[108:109]
	v_pk_mul_f32 v[102:103], v[102:103], v[110:111]
	v_pk_mul_f32 v[104:105], v[96:97], v[104:105]
	v_pk_mul_f32 v[106:107], v[98:99], v[106:107]
; __device__ __forceinline__ unsigned cvt_pk_bf16(float lo, float hi) { cvf32x2_t v = {lo, hi}; cvbf16x2_t b = __builtin_convertvector(v, cvbf16x2_t); return __builtin_bit_cast(unsigned, b); }
; __device__ __forceinline__ float fsilu(float x) { return x * fsigm(x); }
; __device__ __forceinline__ float row_rs(const float* ssq, int row) { return ssq ? rsqrtf(ssq[row] * (1.f / 1024.f) + RMS_EPS) : 1.f; }
;     __device__ __forceinline__ void operator()(const f32x4 (&acc)[2][2][4][2], const Unit& u, int wr, int wc, int fr, int fq) const {
;     ...
;             for (int m = 0; m < 4; ++m) { const int row = row0 + ai * HALF + m * 16; const float rs = row_rs(ssq, row);
;                 u32x4 w; unsigned pk[4];
; #pragma unroll
;                 for (int n = 0; n < 2; ++n) { const f32x4 g = acc[ai][0][m][n] * rs, up = acc[ai][1][m][n] * rs;
;                     pk[2 * n] = cvt_pk_bf16(fsilu(g[0]) * up[0], fsilu(g[1]) * up[1]); pk[2 * n + 1] = cvt_pk_bf16(fsilu(g[2]) * up[2], fsilu(g[3]) * up[3]); }
;                 w.x = pk[0]; w.y = pk[1]; w.z = pk[2]; w.w = pk[3];
;                 st_wt16(H + (size_t)row * ldh + col0, w); }
	v_cvt_pk_bf16_f32 v96, v100, v101
	v_cvt_pk_bf16_f32 v97, v102, v103
	v_cvt_pk_bf16_f32 v98, v104, v105
	v_cvt_pk_bf16_f32 v99, v106, v107
	global_store_dwordx4 v[114:115], v[96:99], off
	s_nop 1
	s_nop 0
	v_or_b32_e32 v96, 48, v144
	v_mad_i64_i32 v[98:99], s[6:7], v112, s79, v[146:147]
	v_lshl_add_u64 v[98:99], v[98:99], 0, v[148:149]
	v_fmamk_f32 v97, v177, 0x3a800000, v158
	v_mul_f32_e32 v100, 0x4b800000, v97
	v_cmp_gt_f32_e32 vcc, s77, v97
	s_nop 1
	v_cndmask_b32_e32 v97, v97, v100, vcc
	v_rsq_f32_e32 v102, v97
	v_ashrrev_i32_e32 v97, 31, v96
	v_lshl_add_u64 v[100:101], v[96:97], 2, s[12:13]
	v_mul_f32_e32 v97, 0x45800000, v102
	v_cndmask_b32_e32 v102, v102, v97, vcc
	v_pk_mul_f32 v[94:95], v[94:95], v[102:103] op_sel_hi:[1,0]
	v_pk_mul_f32 v[92:93], v[92:93], v[102:103] op_sel_hi:[1,0]
	v_pk_mul_f32 v[90:91], v[90:91], v[102:103] op_sel_hi:[1,0]
	v_pk_mul_f32 v[88:89], v[88:89], v[102:103] op_sel_hi:[1,0]
	v_pk_mul_f32 v[86:87], v[86:87], v[102:103] op_sel_hi:[1,0]
	v_pk_mul_f32 v[84:85], v[84:85], v[102:103] op_sel_hi:[1,0]
	v_pk_mul_f32 v[82:83], v[82:83], v[102:103] op_sel_hi:[1,0]
	v_pk_mul_f32 v[80:81], v[80:81], v[102:103] op_sel_hi:[1,0]
	v_mul_f32_e32 v97, 0xbfb8aa3b, v92
	v_mul_f32_e32 v102, 0xbfb8aa3b, v93
	v_mul_f32_e32 v103, 0xbfb8aa3b, v94
	v_mul_f32_e32 v104, 0xbfb8aa3b, v95
	v_mul_f32_e32 v105, 0xbfb8aa3b, v88
	v_mul_f32_e32 v106, 0xbfb8aa3b, v89
	v_mul_f32_e32 v107, 0xbfb8aa3b, v90
	v_mul_f32_e32 v108, 0xbfb8aa3b, v91
	v_exp_f32_e32 v97, v97
	v_exp_f32_e32 v102, v102
	v_exp_f32_e32 v103, v103
	v_exp_f32_e32 v104, v104
	v_exp_f32_e32 v105, v105
	v_exp_f32_e32 v106, v106
	v_exp_f32_e32 v107, v107
	v_exp_f32_e32 v108, v108
	v_add_f32_e32 v97, 1.0, v97
	v_add_f32_e32 v109, 1.0, v102
	v_add_f32_e32 v110, 1.0, v103
	v_add_f32_e32 v111, 1.0, v104
	v_add_f32_e32 v112, 1.0, v105
	v_add_f32_e32 v113, 1.0, v106
	v_add_f32_e32 v114, 1.0, v107
	v_add_f32_e32 v115, 1.0, v108
	v_rcp_f32_e32 v102, v97
	v_rcp_f32_e32 v103, v109
	v_rcp_f32_e32 v104, v110
	v_rcp_f32_e32 v105, v111
	v_rcp_f32_e32 v106, v112
	v_rcp_f32_e32 v107, v113
	v_rcp_f32_e32 v108, v114
	v_rcp_f32_e32 v109, v115
	v_pk_mul_f32 v[92:93], v[92:93], v[102:103]
	v_pk_mul_f32 v[94:95], v[94:95], v[104:105]
	v_pk_mul_f32 v[88:89], v[88:89], v[106:107]
	v_pk_mul_f32 v[90:91], v[90:91], v[108:109]
	v_pk_mul_f32 v[84:85], v[84:85], v[92:93]
	v_pk_mul_f32 v[86:87], v[86:87], v[94:95]
	v_pk_mul_f32 v[88:89], v[80:81], v[88:89]
	v_pk_mul_f32 v[90:91], v[82:83], v[90:91]
	v_cvt_pk_bf16_f32 v80, v84, v85
	v_cvt_pk_bf16_f32 v81, v86, v87
	v_cvt_pk_bf16_f32 v82, v88, v89
	v_cvt_pk_bf16_f32 v83, v90, v91
	global_store_dwordx4 v[98:99], v[80:83], off
	s_nop 1
	v_fmamk_f32 v80, v178, 0x3a800000, v158
	v_mul_f32_e32 v81, 0x4b800000, v80
	v_cmp_gt_f32_e32 vcc, s77, v80
	s_nop 1
	v_cndmask_b32_e32 v80, v80, v81, vcc
	v_rsq_f32_e32 v82, v80
	v_mad_i64_i32 v[80:81], s[6:7], v96, s79, v[146:147]
	v_lshl_add_u64 v[80:81], v[80:81], 0, v[148:149]
	v_mul_f32_e32 v83, 0x45800000, v82
	v_cndmask_b32_e32 v82, v82, v83, vcc
	v_pk_mul_f32 v[78:79], v[78:79], v[82:83] op_sel_hi:[1,0]
	v_pk_mul_f32 v[76:77], v[76:77], v[82:83] op_sel_hi:[1,0]
	v_pk_mul_f32 v[74:75], v[74:75], v[82:83] op_sel_hi:[1,0]
	v_pk_mul_f32 v[72:73], v[72:73], v[82:83] op_sel_hi:[1,0]
	v_pk_mul_f32 v[70:71], v[70:71], v[82:83] op_sel_hi:[1,0]
	v_pk_mul_f32 v[68:69], v[68:69], v[82:83] op_sel_hi:[1,0]
	v_pk_mul_f32 v[66:67], v[66:67], v[82:83] op_sel_hi:[1,0]
	v_pk_mul_f32 v[64:65], v[64:65], v[82:83] op_sel_hi:[1,0]
	v_mul_f32_e32 v82, 0xbfb8aa3b, v76
	v_mul_f32_e32 v83, 0xbfb8aa3b, v77
	v_mul_f32_e32 v84, 0xbfb8aa3b, v78
	v_mul_f32_e32 v85, 0xbfb8aa3b, v79
	v_mul_f32_e32 v86, 0xbfb8aa3b, v72
	v_mul_f32_e32 v87, 0xbfb8aa3b, v73
	v_mul_f32_e32 v88, 0xbfb8aa3b, v74
	v_mul_f32_e32 v89, 0xbfb8aa3b, v75
	v_exp_f32_e32 v82, v82
	v_exp_f32_e32 v83, v83
	v_exp_f32_e32 v84, v84
	v_exp_f32_e32 v85, v85
	v_exp_f32_e32 v86, v86
	v_exp_f32_e32 v87, v87
	v_exp_f32_e32 v88, v88
	v_exp_f32_e32 v89, v89
	v_add_f32_e32 v82, 1.0, v82
	v_add_f32_e32 v83, 1.0, v83
	v_add_f32_e32 v84, 1.0, v84
	v_add_f32_e32 v85, 1.0, v85
	v_add_f32_e32 v86, 1.0, v86
	v_add_f32_e32 v87, 1.0, v87
	v_add_f32_e32 v88, 1.0, v88
	v_add_f32_e32 v89, 1.0, v89
	v_rcp_f32_e32 v82, v82
	v_rcp_f32_e32 v83, v83
	v_rcp_f32_e32 v84, v84
	v_rcp_f32_e32 v85, v85
	v_rcp_f32_e32 v86, v86
	v_rcp_f32_e32 v87, v87
	v_rcp_f32_e32 v88, v88
	v_rcp_f32_e32 v89, v89
	v_pk_mul_f32 v[76:77], v[76:77], v[82:83]
	v_pk_mul_f32 v[78:79], v[78:79], v[84:85]
	v_pk_mul_f32 v[72:73], v[72:73], v[86:87]
	v_pk_mul_f32 v[74:75], v[74:75], v[88:89]
	v_pk_mul_f32 v[68:69], v[68:69], v[76:77]
	v_pk_mul_f32 v[70:71], v[70:71], v[78:79]
	v_pk_mul_f32 v[72:73], v[64:65], v[72:73]
	v_pk_mul_f32 v[74:75], v[66:67], v[74:75]
	v_cvt_pk_bf16_f32 v64, v68, v69
	v_cvt_pk_bf16_f32 v65, v70, v71
	v_cvt_pk_bf16_f32 v66, v72, v73
	v_cvt_pk_bf16_f32 v67, v74, v75
	global_store_dwordx4 v[80:81], v[64:67], off
	s_nop 1
	s_nop 0
	v_add_u32_e32 v65, 0x80, v144
	v_fmamk_f32 v64, v179, 0x3a800000, v158
	v_mul_f32_e32 v66, 0x4b800000, v64
	v_cmp_gt_f32_e32 vcc, s77, v64
	s_nop 1
	v_cndmask_b32_e32 v64, v64, v66, vcc
	v_rsq_f32_e32 v66, v64
	v_mad_i64_i32 v[64:65], s[6:7], v65, s79, v[146:147]
	v_lshl_add_u64 v[64:65], v[64:65], 0, v[148:149]
	v_mul_f32_e32 v67, 0x45800000, v66
	v_cndmask_b32_e32 v66, v66, v67, vcc
	v_pk_mul_f32 v[62:63], v[62:63], v[66:67] op_sel_hi:[1,0]
	v_pk_mul_f32 v[60:61], v[60:61], v[66:67] op_sel_hi:[1,0]
	v_pk_mul_f32 v[58:59], v[58:59], v[66:67] op_sel_hi:[1,0]
	v_pk_mul_f32 v[56:57], v[56:57], v[66:67] op_sel_hi:[1,0]
	v_pk_mul_f32 v[54:55], v[54:55], v[66:67] op_sel_hi:[1,0]
; __device__ __forceinline__ unsigned cvt_pk_bf16(float lo, float hi) { cvf32x2_t v = {lo, hi}; cvbf16x2_t b = __builtin_convertvector(v, cvbf16x2_t); return __builtin_bit_cast(unsigned, b); }
; __device__ __forceinline__ float fsilu(float x) { return x * fsigm(x); }
; __device__ __forceinline__ float row_rs(const float* ssq, int row) { return ssq ? rsqrtf(ssq[row] * (1.f / 1024.f) + RMS_EPS) : 1.f; }
;     __device__ __forceinline__ void operator()(const f32x4 (&acc)[2][2][4][2], const Unit& u, int wr, int wc, int fr, int fq) const {
;     ...
;             for (int m = 0; m < 4; ++m) { const int row = row0 + ai * HALF + m * 16; const float rs = row_rs(ssq, row);
;                 u32x4 w; unsigned pk[4];
; #pragma unroll
;                 for (int n = 0; n < 2; ++n) { const f32x4 g = acc[ai][0][m][n] * rs, up = acc[ai][1][m][n] * rs;
;                     pk[2 * n] = cvt_pk_bf16(fsilu(g[0]) * up[0], fsilu(g[1]) * up[1]); pk[2 * n + 1] = cvt_pk_bf16(fsilu(g[2]) * up[2], fsilu(g[3]) * up[3]); }
;                 w.x = pk[0]; w.y = pk[1]; w.z = pk[2]; w.w = pk[3];
;                 st_wt16(H + (size_t)row * ldh + col0, w); }
	v_pk_mul_f32 v[52:53], v[52:53], v[66:67] op_sel_hi:[1,0]
	v_pk_mul_f32 v[50:51], v[50:51], v[66:67] op_sel_hi:[1,0]
	v_pk_mul_f32 v[48:49], v[48:49], v[66:67] op_sel_hi:[1,0]
	v_mul_f32_e32 v66, 0xbfb8aa3b, v60
	v_mul_f32_e32 v67, 0xbfb8aa3b, v61
	v_mul_f32_e32 v68, 0xbfb8aa3b, v62
	v_mul_f32_e32 v69, 0xbfb8aa3b, v63
	v_mul_f32_e32 v70, 0xbfb8aa3b, v56
	v_mul_f32_e32 v71, 0xbfb8aa3b, v57
	v_mul_f32_e32 v72, 0xbfb8aa3b, v58
	v_mul_f32_e32 v73, 0xbfb8aa3b, v59
	v_exp_f32_e32 v66, v66
	v_exp_f32_e32 v67, v67
	v_exp_f32_e32 v68, v68
	v_exp_f32_e32 v69, v69
	v_exp_f32_e32 v70, v70
	v_exp_f32_e32 v71, v71
	v_exp_f32_e32 v72, v72
	v_exp_f32_e32 v73, v73
	v_add_f32_e32 v66, 1.0, v66
	v_add_f32_e32 v67, 1.0, v67
	v_add_f32_e32 v68, 1.0, v68
	v_add_f32_e32 v69, 1.0, v69
	v_add_f32_e32 v70, 1.0, v70
	v_add_f32_e32 v71, 1.0, v71
	v_add_f32_e32 v72, 1.0, v72
	v_add_f32_e32 v73, 1.0, v73
	v_rcp_f32_e32 v66, v66
	v_rcp_f32_e32 v67, v67
	v_rcp_f32_e32 v68, v68
	v_rcp_f32_e32 v69, v69
	v_rcp_f32_e32 v70, v70
	v_rcp_f32_e32 v71, v71
	v_rcp_f32_e32 v72, v72
	v_rcp_f32_e32 v73, v73
	v_pk_mul_f32 v[60:61], v[60:61], v[66:67]
	v_pk_mul_f32 v[62:63], v[62:63], v[68:69]
	v_pk_mul_f32 v[56:57], v[56:57], v[70:71]
	v_pk_mul_f32 v[58:59], v[58:59], v[72:73]
	v_pk_mul_f32 v[52:53], v[52:53], v[60:61]
	v_pk_mul_f32 v[54:55], v[54:55], v[62:63]
	v_pk_mul_f32 v[56:57], v[48:49], v[56:57]
	v_pk_mul_f32 v[58:59], v[50:51], v[58:59]
	v_cvt_pk_bf16_f32 v48, v52, v53
	v_cvt_pk_bf16_f32 v49, v54, v55
	v_cvt_pk_bf16_f32 v50, v56, v57
	v_cvt_pk_bf16_f32 v51, v58, v59
	global_store_dwordx4 v[64:65], v[48:51], off
	s_nop 1
	s_nop 0
	v_add_u32_e32 v49, 0x90, v144
	v_fmamk_f32 v48, v180, 0x3a800000, v158
	v_mul_f32_e32 v50, 0x4b800000, v48
	v_cmp_gt_f32_e32 vcc, s77, v48
	s_nop 1
	v_cndmask_b32_e32 v48, v48, v50, vcc
	v_rsq_f32_e32 v50, v48
	v_mad_i64_i32 v[48:49], s[6:7], v49, s79, v[146:147]
	v_lshl_add_u64 v[48:49], v[48:49], 0, v[148:149]
	v_mul_f32_e32 v51, 0x45800000, v50
	v_cndmask_b32_e32 v50, v50, v51, vcc
	v_pk_mul_f32 v[46:47], v[46:47], v[50:51] op_sel_hi:[1,0]
	v_pk_mul_f32 v[44:45], v[44:45], v[50:51] op_sel_hi:[1,0]
	v_pk_mul_f32 v[42:43], v[42:43], v[50:51] op_sel_hi:[1,0]
	v_pk_mul_f32 v[40:41], v[40:41], v[50:51] op_sel_hi:[1,0]
	v_pk_mul_f32 v[38:39], v[38:39], v[50:51] op_sel_hi:[1,0]
	v_pk_mul_f32 v[36:37], v[36:37], v[50:51] op_sel_hi:[1,0]
	v_pk_mul_f32 v[34:35], v[34:35], v[50:51] op_sel_hi:[1,0]
	v_pk_mul_f32 v[32:33], v[32:33], v[50:51] op_sel_hi:[1,0]
	v_mul_f32_e32 v50, 0xbfb8aa3b, v44
	v_mul_f32_e32 v51, 0xbfb8aa3b, v45
	v_mul_f32_e32 v52, 0xbfb8aa3b, v46
	v_mul_f32_e32 v53, 0xbfb8aa3b, v47
	v_mul_f32_e32 v54, 0xbfb8aa3b, v40
	v_mul_f32_e32 v55, 0xbfb8aa3b, v41
	v_mul_f32_e32 v56, 0xbfb8aa3b, v42
	v_mul_f32_e32 v57, 0xbfb8aa3b, v43
	v_exp_f32_e32 v50, v50
	v_exp_f32_e32 v51, v51
	v_exp_f32_e32 v52, v52
	v_exp_f32_e32 v53, v53
	v_exp_f32_e32 v54, v54
	v_exp_f32_e32 v55, v55
	v_exp_f32_e32 v56, v56
	v_exp_f32_e32 v57, v57
	v_add_f32_e32 v50, 1.0, v50
	v_add_f32_e32 v51, 1.0, v51
	v_add_f32_e32 v52, 1.0, v52
	v_add_f32_e32 v53, 1.0, v53
	v_add_f32_e32 v54, 1.0, v54
	v_add_f32_e32 v55, 1.0, v55
	v_add_f32_e32 v56, 1.0, v56
	v_add_f32_e32 v57, 1.0, v57
	v_rcp_f32_e32 v50, v50
	v_rcp_f32_e32 v51, v51
	v_rcp_f32_e32 v52, v52
	v_rcp_f32_e32 v53, v53
	v_rcp_f32_e32 v54, v54
	v_rcp_f32_e32 v55, v55
	v_rcp_f32_e32 v56, v56
	v_rcp_f32_e32 v57, v57
	v_pk_mul_f32 v[44:45], v[44:45], v[50:51]
	v_pk_mul_f32 v[46:47], v[46:47], v[52:53]
	v_pk_mul_f32 v[40:41], v[40:41], v[54:55]
	v_pk_mul_f32 v[42:43], v[42:43], v[56:57]
	v_pk_mul_f32 v[36:37], v[36:37], v[44:45]
	v_pk_mul_f32 v[38:39], v[38:39], v[46:47]
	v_pk_mul_f32 v[40:41], v[32:33], v[40:41]
	v_pk_mul_f32 v[42:43], v[34:35], v[42:43]
	v_cvt_pk_bf16_f32 v32, v36, v37
	v_cvt_pk_bf16_f32 v33, v38, v39
	v_cvt_pk_bf16_f32 v34, v40, v41
	v_cvt_pk_bf16_f32 v35, v42, v43
	global_store_dwordx4 v[48:49], v[32:35], off
	s_nop 1
	s_nop 0
	v_add_u32_e32 v33, 0xa0, v144
	v_fmamk_f32 v32, v181, 0x3a800000, v158
	v_mul_f32_e32 v34, 0x4b800000, v32
	v_cmp_gt_f32_e32 vcc, s77, v32
	s_nop 1
	v_cndmask_b32_e32 v32, v32, v34, vcc
	v_rsq_f32_e32 v34, v32
	v_mad_i64_i32 v[32:33], s[6:7], v33, s79, v[146:147]
	v_lshl_add_u64 v[32:33], v[32:33], 0, v[148:149]
	v_mul_f32_e32 v35, 0x45800000, v34
	v_cndmask_b32_e32 v34, v34, v35, vcc
; __device__ __forceinline__ unsigned cvt_pk_bf16(float lo, float hi) { cvf32x2_t v = {lo, hi}; cvbf16x2_t b = __builtin_convertvector(v, cvbf16x2_t); return __builtin_bit_cast(unsigned, b); }
; #define PG8_BAR __builtin_amdgcn_s_barrier()
; __device__ __forceinline__ float fsilu(float x) { return x * fsigm(x); }
; __device__ __forceinline__ float row_rs(const float* ssq, int row) { return ssq ? rsqrtf(ssq[row] * (1.f / 1024.f) + RMS_EPS) : 1.f; }
; template <class Epi, class Sched, bool ALIGN_EPI = false, bool SP2 = false>
; __device__ __forceinline__ void gemm_phase(PG8_LAS unsigned char* lds, const Gemm g, const Sched& S, const Epi& E) {
;     ...
;         }
;         if constexpr (ALIGN_EPI) { if (wr == 0) PG8_BAR; }
;         if constexpr (!Epi::AFTER_DRAIN) { E(acc, cur, wr, wc, fr, fq); S.done(cur); }
;         if (!has_next) break;
; #pragma unroll
;         for (int a = 0; a < 2; ++a)
; #pragma unroll
;             for (int b = 0; b < 2; ++b)
; #pragma unroll
;                 for (int m = 0; m < 4; ++m)
; #pragma unroll
;                     for (int n = 0; n < 2; ++n) acc[a][b][m][n] = (f32x4){0.f, 0.f, 0.f, 0.f};
;         cur = nxt; cA = nA; cB = nB; ++ui;
;         if constexpr (ALIGN_EPI) { if (wr == 1) PG8_BAR; }
;     }
;     __device__ __forceinline__ void operator()(const f32x4 (&acc)[2][2][4][2], const Unit& u, int wr, int wc, int fr, int fq) const {
;     ...
;             for (int m = 0; m < 4; ++m) { const int row = row0 + ai * HALF + m * 16; const float rs = row_rs(ssq, row);
;                 u32x4 w; unsigned pk[4];
; #pragma unroll
;                 for (int n = 0; n < 2; ++n) { const f32x4 g = acc[ai][0][m][n] * rs, up = acc[ai][1][m][n] * rs;
;                     pk[2 * n] = cvt_pk_bf16(fsilu(g[0]) * up[0], fsilu(g[1]) * up[1]); pk[2 * n + 1] = cvt_pk_bf16(fsilu(g[2]) * up[2], fsilu(g[3]) * up[3]); }
;                 w.x = pk[0]; w.y = pk[1]; w.z = pk[2]; w.w = pk[3];
;                 st_wt16(H + (size_t)row * ldh + col0, w); }
	v_pk_mul_f32 v[30:31], v[30:31], v[34:35] op_sel_hi:[1,0]
	v_pk_mul_f32 v[28:29], v[28:29], v[34:35] op_sel_hi:[1,0]
	v_pk_mul_f32 v[26:27], v[26:27], v[34:35] op_sel_hi:[1,0]
	v_pk_mul_f32 v[24:25], v[24:25], v[34:35] op_sel_hi:[1,0]
	v_pk_mul_f32 v[22:23], v[22:23], v[34:35] op_sel_hi:[1,0]
	v_pk_mul_f32 v[20:21], v[20:21], v[34:35] op_sel_hi:[1,0]
	v_pk_mul_f32 v[18:19], v[18:19], v[34:35] op_sel_hi:[1,0]
	v_pk_mul_f32 v[16:17], v[16:17], v[34:35] op_sel_hi:[1,0]
	v_mul_f32_e32 v34, 0xbfb8aa3b, v28
	v_mul_f32_e32 v35, 0xbfb8aa3b, v29
	v_mul_f32_e32 v36, 0xbfb8aa3b, v30
	v_mul_f32_e32 v37, 0xbfb8aa3b, v31
	v_mul_f32_e32 v38, 0xbfb8aa3b, v24
	v_mul_f32_e32 v39, 0xbfb8aa3b, v25
	v_mul_f32_e32 v40, 0xbfb8aa3b, v26
	v_mul_f32_e32 v41, 0xbfb8aa3b, v27
	v_exp_f32_e32 v34, v34
	v_exp_f32_e32 v35, v35
	v_exp_f32_e32 v36, v36
	v_exp_f32_e32 v37, v37
	v_exp_f32_e32 v38, v38
	v_exp_f32_e32 v39, v39
	v_exp_f32_e32 v40, v40
	v_exp_f32_e32 v41, v41
	v_add_f32_e32 v34, 1.0, v34
	v_add_f32_e32 v35, 1.0, v35
	v_add_f32_e32 v36, 1.0, v36
	v_add_f32_e32 v37, 1.0, v37
	v_add_f32_e32 v38, 1.0, v38
	v_add_f32_e32 v39, 1.0, v39
	v_add_f32_e32 v40, 1.0, v40
	v_add_f32_e32 v41, 1.0, v41
	v_rcp_f32_e32 v34, v34
	v_rcp_f32_e32 v35, v35
	v_rcp_f32_e32 v36, v36
	v_rcp_f32_e32 v37, v37
	v_rcp_f32_e32 v38, v38
	v_rcp_f32_e32 v39, v39
	v_rcp_f32_e32 v40, v40
	v_rcp_f32_e32 v41, v41
	v_pk_mul_f32 v[28:29], v[28:29], v[34:35]
	v_pk_mul_f32 v[30:31], v[30:31], v[36:37]
	v_pk_mul_f32 v[24:25], v[24:25], v[38:39]
	v_pk_mul_f32 v[26:27], v[26:27], v[40:41]
	v_pk_mul_f32 v[20:21], v[20:21], v[28:29]
	v_pk_mul_f32 v[22:23], v[22:23], v[30:31]
	v_pk_mul_f32 v[24:25], v[16:17], v[24:25]
	v_pk_mul_f32 v[26:27], v[18:19], v[26:27]
	v_cvt_pk_bf16_f32 v16, v20, v21
	v_cvt_pk_bf16_f32 v17, v22, v23
	v_cvt_pk_bf16_f32 v18, v24, v25
	v_cvt_pk_bf16_f32 v19, v26, v27
	global_store_dwordx4 v[32:33], v[16:19], off
	s_nop 1
	s_andn2_b64 vcc, exec, s[4:5]
	v_add_u32_e32 v17, 0xb0, v144
	s_mov_b64 s[4:5], -1
	v_fmamk_f32 v16, v182, 0x3a800000, v158
	v_mul_f32_e32 v18, 0x4b800000, v16
	v_cmp_gt_f32_e64 s[6:7], s77, v16
	s_nop 1
	v_cndmask_b32_e64 v16, v16, v18, s[6:7]
	v_rsq_f32_e32 v18, v16
	v_mad_i64_i32 v[16:17], s[34:35], v17, s79, v[146:147]
	v_lshl_add_u64 v[16:17], v[16:17], 0, v[148:149]
	v_mul_f32_e32 v19, 0x45800000, v18
	v_cndmask_b32_e64 v18, v18, v19, s[6:7]
	v_pk_mul_f32 v[14:15], v[14:15], v[18:19] op_sel_hi:[1,0]
	v_pk_mul_f32 v[12:13], v[12:13], v[18:19] op_sel_hi:[1,0]
	v_pk_mul_f32 v[10:11], v[10:11], v[18:19] op_sel_hi:[1,0]
	v_pk_mul_f32 v[8:9], v[8:9], v[18:19] op_sel_hi:[1,0]
	v_pk_mul_f32 v[6:7], v[6:7], v[18:19] op_sel_hi:[1,0]
	v_pk_mul_f32 v[4:5], v[4:5], v[18:19] op_sel_hi:[1,0]
	v_pk_mul_f32 v[2:3], v[2:3], v[18:19] op_sel_hi:[1,0]
	v_pk_mul_f32 v[0:1], v[0:1], v[18:19] op_sel_hi:[1,0]
	v_mul_f32_e32 v18, 0xbfb8aa3b, v12
	v_mul_f32_e32 v19, 0xbfb8aa3b, v13
	v_mul_f32_e32 v20, 0xbfb8aa3b, v14
	v_mul_f32_e32 v21, 0xbfb8aa3b, v15
	v_mul_f32_e32 v22, 0xbfb8aa3b, v8
	v_mul_f32_e32 v23, 0xbfb8aa3b, v9
	v_mul_f32_e32 v24, 0xbfb8aa3b, v10
	v_mul_f32_e32 v25, 0xbfb8aa3b, v11
	v_exp_f32_e32 v18, v18
	v_exp_f32_e32 v19, v19
	v_exp_f32_e32 v20, v20
	v_exp_f32_e32 v21, v21
	v_exp_f32_e32 v22, v22
	v_exp_f32_e32 v23, v23
	v_exp_f32_e32 v24, v24
	v_exp_f32_e32 v25, v25
	v_add_f32_e32 v18, 1.0, v18
	v_add_f32_e32 v19, 1.0, v19
	v_add_f32_e32 v20, 1.0, v20
	v_add_f32_e32 v21, 1.0, v21
	v_add_f32_e32 v22, 1.0, v22
	v_add_f32_e32 v23, 1.0, v23
	v_add_f32_e32 v24, 1.0, v24
	v_add_f32_e32 v25, 1.0, v25
	v_rcp_f32_e32 v18, v18
	v_rcp_f32_e32 v19, v19
	v_rcp_f32_e32 v20, v20
	v_rcp_f32_e32 v21, v21
	v_rcp_f32_e32 v22, v22
	v_rcp_f32_e32 v23, v23
	v_rcp_f32_e32 v24, v24
	v_rcp_f32_e32 v25, v25
	v_pk_mul_f32 v[12:13], v[12:13], v[18:19]
	v_pk_mul_f32 v[14:15], v[14:15], v[20:21]
	v_pk_mul_f32 v[8:9], v[8:9], v[22:23]
	v_pk_mul_f32 v[10:11], v[10:11], v[24:25]
	v_pk_mul_f32 v[4:5], v[4:5], v[12:13]
	v_pk_mul_f32 v[6:7], v[6:7], v[14:15]
	v_pk_mul_f32 v[8:9], v[0:1], v[8:9]
	v_pk_mul_f32 v[10:11], v[2:3], v[10:11]
	v_cvt_pk_bf16_f32 v0, v4, v5
	v_cvt_pk_bf16_f32 v1, v6, v7
	v_cvt_pk_bf16_f32 v2, v8, v9
	v_cvt_pk_bf16_f32 v3, v10, v11
	global_store_dwordx4 v[16:17], v[0:3], off
	s_cbranch_vccnz .LBB0_1267
	s_andn2_b64 vcc, exec, s[10:11]
	s_cbranch_vccnz .LBB0_1266
	s_barrier
	s_branch .LBB0_1266
